# v14 + b_bar table loads batched (ssm tables) + residual/norm phase after the mixer: the next row's eight fp16 residual segments requested together instead of load-wait-convert per segment
# speedup vs baseline: 1.0087x; 1.0087x over previous
; __device__ __forceinline__ void ssm_tables(const Params& p, const Ctx& c) {
;     ...
;   for (long i = c.gtid; i < 2L * 32 * 2 * 64; i += c.nthr) { const int pp = (int)(i & 63), idx = (int)(i >> 6);
;     const int d = idx & 1, g = (idx >> 1) & 31, l = idx >> 6, iidx = (l * 2 + d) * 32 + g;
;     const float lre = p.ssm_a_re[iidx * 64 + pp], lim = p.ssm_a_im[iidx * 64 + pp], dt = expf(p.ssm_log_dt[iidx]);
;     const float mag = expf(lre * dt); float sn, cs; my_sincos(lim * dt, sn, cs); const float ar = mag * cs, ai = mag * sn;
;     const float nr = ar - 1.f, ni = ai, den = 1.f / (lre * lre + lim * lim), cr = (nr * lre + ni * lim) * den, ci = (ni * lre - nr * lim) * den;
;     const float* br = p.ssm_b_re + ((size_t)iidx * 64 + pp) * 16; const float* bi = p.ssm_b_im + ((size_t)iidx * 64 + pp) * 16;
;     for (int h = 0; h < 16; ++h) BB[((size_t)idx * 64 + pp) * 16 + h] = make_float2(cr * br[h] - ci * bi[h], cr * bi[h] + ci * br[h]); }
.LBB0_52:
	s_or_b64 exec, exec, s[62:63]
	v_lshlrev_b64 v[10:11], 12, v[10:11]
	v_lshl_or_b32 v10, v2, 2, v10
	v_lshl_add_u64 v[16:17], s[14:15], 0, v[10:11]
	v_lshl_add_u64 v[10:11], s[20:21], 0, v[10:11]
	global_load_dword v126, v[10:11], off
	global_load_dword v127, v[10:11], off offset:4
	global_load_dword v128, v[10:11], off offset:8
	global_load_dword v129, v[10:11], off offset:12
	global_load_dword v130, v[10:11], off offset:16
	global_load_dword v131, v[10:11], off offset:20
	global_load_dword v132, v[10:11], off offset:24
	global_load_dword v133, v[10:11], off offset:28
	global_load_dword v134, v[10:11], off offset:32
	global_load_dword v135, v[10:11], off offset:36
	global_load_dword v136, v[10:11], off offset:40
	global_load_dword v137, v[10:11], off offset:44
	global_load_dword v138, v[10:11], off offset:48
	global_load_dword v139, v[10:11], off offset:52
	global_load_dword v140, v[10:11], off offset:56
	global_load_dword v141, v[10:11], off offset:60
	s_waitcnt vmcnt(15)
	v_mov_b32_e32 v18, v126
	global_load_dword v142, v[16:17], off
	global_load_dword v143, v[16:17], off offset:4
	global_load_dword v144, v[16:17], off offset:8
	global_load_dword v145, v[16:17], off offset:12
	global_load_dword v146, v[16:17], off offset:16
	global_load_dword v147, v[16:17], off offset:20
	global_load_dword v148, v[16:17], off offset:24
	global_load_dword v149, v[16:17], off offset:28
	global_load_dword v150, v[16:17], off offset:32
	global_load_dword v151, v[16:17], off offset:36
	global_load_dword v152, v[16:17], off offset:40
	global_load_dword v153, v[16:17], off offset:44
	global_load_dword v154, v[16:17], off offset:48
	global_load_dword v155, v[16:17], off offset:52
	global_load_dword v156, v[16:17], off offset:56
	global_load_dword v157, v[16:17], off offset:60
	s_waitcnt vmcnt(32)
	s_waitcnt vmcnt(15)
	v_mov_b32_e32 v20, v142
	v_mul_f32_e32 v9, v4, v1
	v_lshrrev_b64 v[22:23], 6, v[6:7]
	v_cvt_f32_f64_e32 v19, v[12:13]
	v_cvt_f32_f64_e32 v15, v[14:15]
	v_pk_mul_f32 v[12:13], v[4:5], v[4:5]
	v_mov_b32_e32 v14, v5
	v_mul_f32_e32 v5, 0x3fb8aa3b, v9
	v_add_f32_e32 v21, v12, v13
	v_mov_b32_e32 v1, v22
	v_fma_f32 v22, v9, s0, -v5
	v_rndne_f32_e32 v23, v5
	v_div_scale_f32 v24, s[4:5], v21, v21, 1.0
	v_ashrrev_i64 v[12:13], 26, v[0:1]
	v_fmac_f32_e32 v22, 0x32a5705f, v9
	v_sub_f32_e32 v1, v5, v23
	v_rcp_f32_e32 v26, v24
	v_add_f32_e32 v1, v1, v22
	v_cvt_i32_f32_e32 v5, v23
	v_exp_f32_e32 v1, v1
	v_fma_f32 v22, -v24, v26, 1.0
	v_div_scale_f32 v25, vcc, 1.0, v21, 1.0
	v_fmac_f32_e32 v26, v22, v26
	v_ldexp_f32 v1, v1, v5
	v_cmp_ngt_f32_e64 s[4:5], s1, v9
	v_mul_f32_e32 v5, v25, v26
	v_fma_f32 v22, -v24, v5, v25
	v_cndmask_b32_e64 v1, 0, v1, s[4:5]
	v_cmp_nlt_f32_e64 s[4:5], s2, v9
	v_fmac_f32_e32 v5, v22, v26
	v_or_b32_e32 v12, v12, v8
	v_cndmask_b32_e64 v1, v3, v1, s[4:5]
	v_mul_f32_e32 v23, v1, v19
	v_fma_f32 v22, v1, v15, -1.0
	v_fma_f32 v1, -v24, v5, v25
	v_pk_mul_f32 v[14:15], v[14:15], v[22:23] op_sel:[0,1] op_sel_hi:[0,0]
	v_div_fmas_f32 v1, v1, v26, v5
	v_pk_fma_f32 v[26:27], v[4:5], v[22:23], v[14:15]
	v_pk_fma_f32 v[4:5], v[4:5], v[22:23], v[14:15] op_sel_hi:[0,1,1] neg_lo:[0,0,1] neg_hi:[0,0,1]
	v_div_fixup_f32 v24, v1, v21, 1.0
	v_mov_b32_e32 v27, v5
	v_pk_mul_f32 v[4:5], v[24:25], v[26:27] op_sel_hi:[0,1]
	v_lshlrev_b64 v[12:13], 7, v[12:13]
	v_lshl_add_u64 v[12:13], s[18:19], 0, v[12:13]
	v_lshl_add_u64 v[6:7], v[6:7], 0, s[22:23]
	v_cmp_lt_i64_e32 vcc, s[60:61], v[6:7]
	s_or_b64 s[24:25], vcc, s[24:25]
	v_pk_mul_f32 v[14:15], v[18:19], v[4:5] op_sel:[0,1] op_sel_hi:[0,0]
	v_pk_fma_f32 v[18:19], v[20:21], v[4:5], v[14:15] neg_lo:[0,0,1] neg_hi:[0,0,1]
	v_pk_fma_f32 v[14:15], v[20:21], v[4:5], v[14:15] op_sel_hi:[0,1,1]
	v_mov_b32_e32 v19, v15
	global_store_dwordx2 v[12:13], v[18:19], off
	s_waitcnt vmcnt(31)
	v_mov_b32_e32 v14, v127
	s_nop 0
	s_waitcnt vmcnt(15)
	v_mov_b32_e32 v18, v143
	v_pk_mul_f32 v[14:15], v[4:5], v[14:15] op_sel:[1,0] op_sel_hi:[0,0]
	v_pk_fma_f32 v[20:21], v[4:5], v[18:19], v[14:15] neg_lo:[0,0,1] neg_hi:[0,0,1]
	v_pk_fma_f32 v[14:15], v[4:5], v[18:19], v[14:15] op_sel_hi:[1,0,1]
	s_nop 0
	v_mov_b32_e32 v21, v15
	global_store_dwordx2 v[12:13], v[20:21], off offset:8
	s_waitcnt vmcnt(31)
	v_mov_b32_e32 v14, v128
	s_waitcnt vmcnt(15)
	v_mov_b32_e32 v18, v144
	v_pk_mul_f32 v[14:15], v[4:5], v[14:15] op_sel:[1,0] op_sel_hi:[0,0]
	v_pk_fma_f32 v[20:21], v[4:5], v[18:19], v[14:15] neg_lo:[0,0,1] neg_hi:[0,0,1]
	v_pk_fma_f32 v[14:15], v[4:5], v[18:19], v[14:15] op_sel_hi:[1,0,1]
	s_nop 0
	v_mov_b32_e32 v21, v15
	global_store_dwordx2 v[12:13], v[20:21], off offset:16
	s_waitcnt vmcnt(31)
	v_mov_b32_e32 v14, v129
	s_waitcnt vmcnt(15)
	v_mov_b32_e32 v18, v145
	v_pk_mul_f32 v[14:15], v[4:5], v[14:15] op_sel:[1,0] op_sel_hi:[0,0]
	v_pk_fma_f32 v[20:21], v[4:5], v[18:19], v[14:15] neg_lo:[0,0,1] neg_hi:[0,0,1]
	v_pk_fma_f32 v[14:15], v[4:5], v[18:19], v[14:15] op_sel_hi:[1,0,1]
	s_nop 0
	v_mov_b32_e32 v21, v15
	global_store_dwordx2 v[12:13], v[20:21], off offset:24
	s_waitcnt vmcnt(31)
; __device__ __forceinline__ void ssm_tables(const Params& p, const Ctx& c) {
;     ...
;   for (long i = c.gtid; i < 2L * 32 * 2 * 64; i += c.nthr) { const int pp = (int)(i & 63), idx = (int)(i >> 6);
;     const int d = idx & 1, g = (idx >> 1) & 31, l = idx >> 6, iidx = (l * 2 + d) * 32 + g;
;     const float lre = p.ssm_a_re[iidx * 64 + pp], lim = p.ssm_a_im[iidx * 64 + pp], dt = expf(p.ssm_log_dt[iidx]);
;     const float mag = expf(lre * dt); float sn, cs; my_sincos(lim * dt, sn, cs); const float ar = mag * cs, ai = mag * sn;
;     const float nr = ar - 1.f, ni = ai, den = 1.f / (lre * lre + lim * lim), cr = (nr * lre + ni * lim) * den, ci = (ni * lre - nr * lim) * den;
;     const float* br = p.ssm_b_re + ((size_t)iidx * 64 + pp) * 16; const float* bi = p.ssm_b_im + ((size_t)iidx * 64 + pp) * 16;
;     for (int h = 0; h < 16; ++h) BB[((size_t)idx * 64 + pp) * 16 + h] = make_float2(cr * br[h] - ci * bi[h], cr * bi[h] + ci * br[h]); }
	v_mov_b32_e32 v14, v130
	s_waitcnt vmcnt(15)
	v_mov_b32_e32 v18, v146
	v_pk_mul_f32 v[14:15], v[4:5], v[14:15] op_sel:[1,0] op_sel_hi:[0,0]
	v_pk_fma_f32 v[20:21], v[4:5], v[18:19], v[14:15] neg_lo:[0,0,1] neg_hi:[0,0,1]
	v_pk_fma_f32 v[14:15], v[4:5], v[18:19], v[14:15] op_sel_hi:[1,0,1]
	s_nop 0
	v_mov_b32_e32 v21, v15
	global_store_dwordx2 v[12:13], v[20:21], off offset:32
	s_waitcnt vmcnt(31)
	v_mov_b32_e32 v14, v131
	s_waitcnt vmcnt(15)
	v_mov_b32_e32 v18, v147
	v_pk_mul_f32 v[14:15], v[4:5], v[14:15] op_sel:[1,0] op_sel_hi:[0,0]
	v_pk_fma_f32 v[20:21], v[4:5], v[18:19], v[14:15] neg_lo:[0,0,1] neg_hi:[0,0,1]
	v_pk_fma_f32 v[14:15], v[4:5], v[18:19], v[14:15] op_sel_hi:[1,0,1]
	s_nop 0
	v_mov_b32_e32 v21, v15
	global_store_dwordx2 v[12:13], v[20:21], off offset:40
	s_waitcnt vmcnt(31)
	v_mov_b32_e32 v14, v132
	s_waitcnt vmcnt(15)
	v_mov_b32_e32 v18, v148
	v_pk_mul_f32 v[14:15], v[4:5], v[14:15] op_sel:[1,0] op_sel_hi:[0,0]
	v_pk_fma_f32 v[20:21], v[4:5], v[18:19], v[14:15] neg_lo:[0,0,1] neg_hi:[0,0,1]
	v_pk_fma_f32 v[14:15], v[4:5], v[18:19], v[14:15] op_sel_hi:[1,0,1]
	s_nop 0
	v_mov_b32_e32 v21, v15
	global_store_dwordx2 v[12:13], v[20:21], off offset:48
	s_waitcnt vmcnt(31)
	v_mov_b32_e32 v14, v133
	s_waitcnt vmcnt(15)
	v_mov_b32_e32 v18, v149
	v_pk_mul_f32 v[14:15], v[4:5], v[14:15] op_sel:[1,0] op_sel_hi:[0,0]
	v_pk_fma_f32 v[20:21], v[4:5], v[18:19], v[14:15] neg_lo:[0,0,1] neg_hi:[0,0,1]
	v_pk_fma_f32 v[14:15], v[4:5], v[18:19], v[14:15] op_sel_hi:[1,0,1]
	s_nop 0
	v_mov_b32_e32 v21, v15
	global_store_dwordx2 v[12:13], v[20:21], off offset:56
	s_waitcnt vmcnt(31)
	v_mov_b32_e32 v14, v134
	s_waitcnt vmcnt(15)
	v_mov_b32_e32 v18, v150
	v_pk_mul_f32 v[14:15], v[4:5], v[14:15] op_sel:[1,0] op_sel_hi:[0,0]
	v_pk_fma_f32 v[20:21], v[4:5], v[18:19], v[14:15] neg_lo:[0,0,1] neg_hi:[0,0,1]
	v_pk_fma_f32 v[14:15], v[4:5], v[18:19], v[14:15] op_sel_hi:[1,0,1]
	s_nop 0
	v_mov_b32_e32 v21, v15
	global_store_dwordx2 v[12:13], v[20:21], off offset:64
	s_waitcnt vmcnt(31)
	v_mov_b32_e32 v14, v135
	s_waitcnt vmcnt(15)
	v_mov_b32_e32 v18, v151
	v_pk_mul_f32 v[14:15], v[4:5], v[14:15] op_sel:[1,0] op_sel_hi:[0,0]
	v_pk_fma_f32 v[20:21], v[4:5], v[18:19], v[14:15] neg_lo:[0,0,1] neg_hi:[0,0,1]
	v_pk_fma_f32 v[14:15], v[4:5], v[18:19], v[14:15] op_sel_hi:[1,0,1]
	s_nop 0
	v_mov_b32_e32 v21, v15
	global_store_dwordx2 v[12:13], v[20:21], off offset:72
	s_waitcnt vmcnt(31)
	v_mov_b32_e32 v14, v136
	s_waitcnt vmcnt(15)
	v_mov_b32_e32 v18, v152
	v_pk_mul_f32 v[14:15], v[4:5], v[14:15] op_sel:[1,0] op_sel_hi:[0,0]
	v_pk_fma_f32 v[20:21], v[4:5], v[18:19], v[14:15] neg_lo:[0,0,1] neg_hi:[0,0,1]
	v_pk_fma_f32 v[14:15], v[4:5], v[18:19], v[14:15] op_sel_hi:[1,0,1]
	s_nop 0
	v_mov_b32_e32 v21, v15
	global_store_dwordx2 v[12:13], v[20:21], off offset:80
	s_waitcnt vmcnt(31)
	v_mov_b32_e32 v14, v137
	s_waitcnt vmcnt(15)
	v_mov_b32_e32 v18, v153
	v_pk_mul_f32 v[14:15], v[4:5], v[14:15] op_sel:[1,0] op_sel_hi:[0,0]
	v_pk_fma_f32 v[20:21], v[4:5], v[18:19], v[14:15] neg_lo:[0,0,1] neg_hi:[0,0,1]
	v_pk_fma_f32 v[14:15], v[4:5], v[18:19], v[14:15] op_sel_hi:[1,0,1]
	s_nop 0
	v_mov_b32_e32 v21, v15
	global_store_dwordx2 v[12:13], v[20:21], off offset:88
	s_waitcnt vmcnt(31)
	v_mov_b32_e32 v14, v138
	s_waitcnt vmcnt(15)
	v_mov_b32_e32 v18, v154
	v_pk_mul_f32 v[14:15], v[4:5], v[14:15] op_sel:[1,0] op_sel_hi:[0,0]
	v_pk_fma_f32 v[20:21], v[4:5], v[18:19], v[14:15] neg_lo:[0,0,1] neg_hi:[0,0,1]
	v_pk_fma_f32 v[14:15], v[4:5], v[18:19], v[14:15] op_sel_hi:[1,0,1]
	s_nop 0
	v_mov_b32_e32 v21, v15
	global_store_dwordx2 v[12:13], v[20:21], off offset:96
	s_waitcnt vmcnt(31)
	v_mov_b32_e32 v14, v139
	s_waitcnt vmcnt(15)
	v_mov_b32_e32 v18, v155
	v_pk_mul_f32 v[14:15], v[4:5], v[14:15] op_sel:[1,0] op_sel_hi:[0,0]
	v_pk_fma_f32 v[20:21], v[4:5], v[18:19], v[14:15] neg_lo:[0,0,1] neg_hi:[0,0,1]
	v_pk_fma_f32 v[14:15], v[4:5], v[18:19], v[14:15] op_sel_hi:[1,0,1]
	s_nop 0
	v_mov_b32_e32 v21, v15
	global_store_dwordx2 v[12:13], v[20:21], off offset:104
	s_waitcnt vmcnt(31)
	v_mov_b32_e32 v14, v140
	s_waitcnt vmcnt(15)
	v_mov_b32_e32 v18, v156
	v_pk_mul_f32 v[14:15], v[4:5], v[14:15] op_sel:[1,0] op_sel_hi:[0,0]
	v_pk_fma_f32 v[20:21], v[4:5], v[18:19], v[14:15] neg_lo:[0,0,1] neg_hi:[0,0,1]
	v_pk_fma_f32 v[14:15], v[4:5], v[18:19], v[14:15] op_sel_hi:[1,0,1]
	s_nop 0
	v_mov_b32_e32 v21, v15
	global_store_dwordx2 v[12:13], v[20:21], off offset:112
	s_waitcnt vmcnt(31)
	v_mov_b32_e32 v10, v141
	s_nop 0
	s_waitcnt vmcnt(15)
	v_mov_b32_e32 v14, v157
	v_pk_mul_f32 v[10:11], v[4:5], v[10:11] op_sel:[1,0] op_sel_hi:[0,0]
	v_pk_fma_f32 v[16:17], v[4:5], v[14:15], v[10:11] neg_lo:[0,0,1] neg_hi:[0,0,1]
	v_pk_fma_f32 v[4:5], v[4:5], v[14:15], v[10:11] op_sel_hi:[1,0,1]
	s_nop 0
	v_mov_b32_e32 v17, v5
	global_store_dwordx2 v[12:13], v[16:17], off offset:120
	s_andn2_b64 exec, exec, s[24:25]
	s_cbranch_execz .LBB0_56

; __device__ __forceinline__ f32x4 ldx(const _Float16* p) { const h16x4 h = *(const h16x4*)p; return __builtin_convertvector(h, f32x4); }
; __device__ __forceinline__ f32x4 bf4(const u32x2 w) { return (f32x4){__uint_as_float(w[0] << 16), __uint_as_float(w[0] & 0xffff0000u), __uint_as_float(w[1] << 16), __uint_as_float(w[1] & 0xffff0000u)}; }
; __device__ __forceinline__ void phase_postmix(const Params& p, const Ctx& c, int l, bool last) {
;     ...
;   auto load = [&](int row, f32x4 (&m)[8], f32x4 (&x)[8]) { const int b = row / TPB, t = row % TPB;
;     const u32x2* mr = (const u32x2*)(MIX + (size_t)row * DM); const _Float16* xr = X + (size_t)row * DM; const f32x4* xs = (const f32x4*)xrow_src(p, 0, b, t, row);
;     if (t < CTXL) { const u32x2* sl = (const u32x2*)(p.ws + OFF_Z2) + ((size_t)b * CTXL + t) * (DM / 4);
; #pragma unroll
;       for (int i = 0; i < 8; ++i) { m[i] = (f32x4){0.f, 0.f, 0.f, 0.f}; x[i] = xs[c.lane + 64 * i]; }
;       for (int s = 0; s < 8; ++s) {
; #pragma unroll
;         for (int i = 0; i < 8; ++i) m[i] += bf4(sl[(size_t)s * NB * CTXL * (DM / 4) + c.lane + 64 * i]); } }
;     else {
; #pragma unroll
;       for (int i = 0; i < 8; ++i) { m[i] = bf4(mr[c.lane + 64 * i]); x[i] = (l == 0) ? xs[c.lane + 64 * i] : ldx(xr + (c.lane + 64 * i) * 4); } } };
.LBB0_1022:
	s_or_b64 exec, exec, s[58:59]
	s_xor_b64 s[0:1], s[56:57], -1
	s_xor_b64 s[62:63], s[60:61], -1
	s_mov_b64 s[56:57], 0
	s_and_saveexec_b64 s[2:3], s[0:1]
	s_xor_b64 s[58:59], exec, s[2:3]
	s_cbranch_execz .LBB0_1061
	v_cndmask_b32_e64 v34, 0, 16, s[60:61]
	v_mov_b32_e32 v35, v0
	v_lshl_add_u64 v[34:35], s[84:85], 0, v[34:35]
	global_load_dwordx2 v[34:35], v[34:35], off
	v_add_u32_e32 v36, 0xffffff00, v66
	v_ashrrev_i32_e32 v37, 31, v66
	v_cndmask_b32_e64 v37, 0, v37, s[60:61]
	v_cndmask_b32_e64 v36, v36, v66, s[60:61]
	v_ashrrev_i32_e32 v69, 31, v68
	v_cndmask_b32_e64 v38, 23, 19, s[60:61]
	v_lshlrev_b64 v[36:37], 13, v[36:37]
	v_lshlrev_b64 v[38:39], v38, v[68:69]
	s_waitcnt vmcnt(0)
	v_lshl_add_u64 v[34:35], v[34:35], 0, v[36:37]
	v_lshl_add_u64 v[66:67], v[38:39], 2, v[34:35]
	s_and_saveexec_b64 s[0:1], s[62:63]
	s_xor_b64 s[56:57], exec, s[0:1]
	s_cbranch_execz .LBB0_1057
	v_ashrrev_i32_e32 v159, 31, v158
	v_lshlrev_b64 v[34:35], 12, v[158:159]
	v_lshl_add_u64 v[62:63], v[128:129], 0, v[34:35]
	global_load_dwordx2 v[68:69], v[62:63], off
	v_readlane_b32 s0, v250, 14
	v_readlane_b32 s1, v250, 15
	v_lshl_add_u64 v[70:71], s[12:13], 0, v[34:35]
	s_mov_b64 s[60:61], -1
	s_and_b64 vcc, exec, s[0:1]
	v_lshlrev_b32_e32 v74, 1, v114
	s_cbranch_vccz .LBB0_1026
	v_mov_b32_e32 v75, v0
	v_lshl_add_u64 v[34:35], v[70:71], 0, v[74:75]
	global_load_dwordx2 v[36:37], v[34:35], off
	global_load_dwordx2 v[40:41], v[34:35], off offset:512
	global_load_dwordx2 v[44:45], v[34:35], off offset:1024
	global_load_dwordx2 v[48:49], v[34:35], off offset:1536
	global_load_dwordx2 v[52:53], v[34:35], off offset:2048
	global_load_dwordx2 v[56:57], v[34:35], off offset:2560
	global_load_dwordx2 v[60:61], v[34:35], off offset:3072
	global_load_dwordx2 v[64:65], v[34:35], off offset:3584
	s_mov_b64 s[60:61], 0
	s_waitcnt vmcnt(7)
	v_cvt_f32_f16_e32 v34, v36
	v_cvt_f32_f16_sdwa v35, v36 dst_sel:DWORD dst_unused:UNUSED_PAD src0_sel:WORD_1
	v_cvt_f32_f16_e32 v36, v37
	v_cvt_f32_f16_sdwa v37, v37 dst_sel:DWORD dst_unused:UNUSED_PAD src0_sel:WORD_1

; __device__ __forceinline__ f32x4 ldx(const _Float16* p) { const h16x4 h = *(const h16x4*)p; return __builtin_convertvector(h, f32x4); }
; __device__ __forceinline__ f32x4 bf4(const u32x2 w) { return (f32x4){__uint_as_float(w[0] << 16), __uint_as_float(w[0] & 0xffff0000u), __uint_as_float(w[1] << 16), __uint_as_float(w[1] & 0xffff0000u)}; }
; __device__ __forceinline__ void phase_postmix(const Params& p, const Ctx& c, int l, bool last) {
;     ...
; #pragma unroll
;       for (int i = 0; i < 8; ++i) { m[i] = bf4(mr[c.lane + 64 * i]); x[i] = (l == 0) ? xs[c.lane + 64 * i] : ldx(xr + (c.lane + 64 * i) * 4); } } };
.LBB0_1028:
	s_nop 0
	global_load_dwordx2 v[72:73], v[62:63], off offset:512
	s_and_b64 vcc, exec, s[0:1]
	s_mov_b64 s[60:61], -1
	s_cbranch_vccnz .LBB0_1030
	s_waitcnt vmcnt(7)
	v_cvt_f32_f16_e32 v38, v40
	v_cvt_f32_f16_sdwa v39, v40 dst_sel:DWORD dst_unused:UNUSED_PAD src0_sel:WORD_1
	v_cvt_f32_f16_e32 v40, v41
	v_cvt_f32_f16_sdwa v41, v41 dst_sel:DWORD dst_unused:UNUSED_PAD src0_sel:WORD_1
	s_cbranch_execnz .LBB0_1032
	s_branch .LBB0_1031

; __device__ __forceinline__ f32x4 ldx(const _Float16* p) { const h16x4 h = *(const h16x4*)p; return __builtin_convertvector(h, f32x4); }
; __device__ __forceinline__ f32x4 bf4(const u32x2 w) { return (f32x4){__uint_as_float(w[0] << 16), __uint_as_float(w[0] & 0xffff0000u), __uint_as_float(w[1] << 16), __uint_as_float(w[1] & 0xffff0000u)}; }
; __device__ __forceinline__ void phase_postmix(const Params& p, const Ctx& c, int l, bool last) {
;     ...
; #pragma unroll
;       for (int i = 0; i < 8; ++i) { m[i] = bf4(mr[c.lane + 64 * i]); x[i] = (l == 0) ? xs[c.lane + 64 * i] : ldx(xr + (c.lane + 64 * i) * 4); } } };
.LBB0_1032:
	s_nop 0
	global_load_dwordx2 v[76:77], v[62:63], off offset:1024
	s_and_b64 vcc, exec, s[0:1]
	s_mov_b64 s[60:61], -1
	s_cbranch_vccnz .LBB0_1034
	s_waitcnt vmcnt(7)
	v_cvt_f32_f16_e32 v42, v44
	v_cvt_f32_f16_sdwa v43, v44 dst_sel:DWORD dst_unused:UNUSED_PAD src0_sel:WORD_1
	v_cvt_f32_f16_e32 v44, v45
	v_cvt_f32_f16_sdwa v45, v45 dst_sel:DWORD dst_unused:UNUSED_PAD src0_sel:WORD_1
	s_cbranch_execnz .LBB0_1036
	s_branch .LBB0_1035

; __device__ __forceinline__ f32x4 ldx(const _Float16* p) { const h16x4 h = *(const h16x4*)p; return __builtin_convertvector(h, f32x4); }
; __device__ __forceinline__ f32x4 bf4(const u32x2 w) { return (f32x4){__uint_as_float(w[0] << 16), __uint_as_float(w[0] & 0xffff0000u), __uint_as_float(w[1] << 16), __uint_as_float(w[1] & 0xffff0000u)}; }
; __device__ __forceinline__ void phase_postmix(const Params& p, const Ctx& c, int l, bool last) {
;     ...
; #pragma unroll
;       for (int i = 0; i < 8; ++i) { m[i] = bf4(mr[c.lane + 64 * i]); x[i] = (l == 0) ? xs[c.lane + 64 * i] : ldx(xr + (c.lane + 64 * i) * 4); } } };
.LBB0_1036:
	s_nop 0
	global_load_dwordx2 v[172:173], v[62:63], off offset:1536
	s_and_b64 vcc, exec, s[0:1]
	s_mov_b64 s[60:61], -1
	s_cbranch_vccnz .LBB0_1038
	s_waitcnt vmcnt(7)
	v_cvt_f32_f16_e32 v46, v48
	v_cvt_f32_f16_sdwa v47, v48 dst_sel:DWORD dst_unused:UNUSED_PAD src0_sel:WORD_1
	v_cvt_f32_f16_e32 v48, v49
	v_cvt_f32_f16_sdwa v49, v49 dst_sel:DWORD dst_unused:UNUSED_PAD src0_sel:WORD_1
	s_cbranch_execnz .LBB0_1040
	s_branch .LBB0_1039

; __device__ __forceinline__ f32x4 ldx(const _Float16* p) { const h16x4 h = *(const h16x4*)p; return __builtin_convertvector(h, f32x4); }
; __device__ __forceinline__ f32x4 bf4(const u32x2 w) { return (f32x4){__uint_as_float(w[0] << 16), __uint_as_float(w[0] & 0xffff0000u), __uint_as_float(w[1] << 16), __uint_as_float(w[1] & 0xffff0000u)}; }
; __device__ __forceinline__ void phase_postmix(const Params& p, const Ctx& c, int l, bool last) {
;     ...
; #pragma unroll
;       for (int i = 0; i < 8; ++i) { m[i] = bf4(mr[c.lane + 64 * i]); x[i] = (l == 0) ? xs[c.lane + 64 * i] : ldx(xr + (c.lane + 64 * i) * 4); } } };
.LBB0_1040:
	s_nop 0
	global_load_dwordx2 v[174:175], v[62:63], off offset:2048
	s_and_b64 vcc, exec, s[0:1]
	s_mov_b64 s[60:61], -1
	s_cbranch_vccnz .LBB0_1042
	s_waitcnt vmcnt(7)
	v_cvt_f32_f16_e32 v50, v52
	v_cvt_f32_f16_sdwa v51, v52 dst_sel:DWORD dst_unused:UNUSED_PAD src0_sel:WORD_1
	v_cvt_f32_f16_e32 v52, v53
	v_cvt_f32_f16_sdwa v53, v53 dst_sel:DWORD dst_unused:UNUSED_PAD src0_sel:WORD_1
	s_cbranch_execnz .LBB0_1044
	s_branch .LBB0_1043

; __device__ __forceinline__ f32x4 ldx(const _Float16* p) { const h16x4 h = *(const h16x4*)p; return __builtin_convertvector(h, f32x4); }
; __device__ __forceinline__ f32x4 bf4(const u32x2 w) { return (f32x4){__uint_as_float(w[0] << 16), __uint_as_float(w[0] & 0xffff0000u), __uint_as_float(w[1] << 16), __uint_as_float(w[1] & 0xffff0000u)}; }
; __device__ __forceinline__ void phase_postmix(const Params& p, const Ctx& c, int l, bool last) {
;     ...
; #pragma unroll
;       for (int i = 0; i < 8; ++i) { m[i] = bf4(mr[c.lane + 64 * i]); x[i] = (l == 0) ? xs[c.lane + 64 * i] : ldx(xr + (c.lane + 64 * i) * 4); } } };
.LBB0_1044:
	s_nop 0
	global_load_dwordx2 v[184:185], v[62:63], off offset:2560
	s_and_b64 vcc, exec, s[0:1]
	s_mov_b64 s[60:61], -1
	s_cbranch_vccnz .LBB0_1046
	s_waitcnt vmcnt(7)
	v_cvt_f32_f16_e32 v54, v56
	v_cvt_f32_f16_sdwa v55, v56 dst_sel:DWORD dst_unused:UNUSED_PAD src0_sel:WORD_1
	v_cvt_f32_f16_e32 v56, v57
	v_cvt_f32_f16_sdwa v57, v57 dst_sel:DWORD dst_unused:UNUSED_PAD src0_sel:WORD_1
	s_cbranch_execnz .LBB0_1048
	s_branch .LBB0_1047

; __device__ __forceinline__ f32x4 ldx(const _Float16* p) { const h16x4 h = *(const h16x4*)p; return __builtin_convertvector(h, f32x4); }
; __device__ __forceinline__ f32x4 bf4(const u32x2 w) { return (f32x4){__uint_as_float(w[0] << 16), __uint_as_float(w[0] & 0xffff0000u), __uint_as_float(w[1] << 16), __uint_as_float(w[1] & 0xffff0000u)}; }
; __device__ __forceinline__ void phase_postmix(const Params& p, const Ctx& c, int l, bool last) {
;     ...
; #pragma unroll
;       for (int i = 0; i < 8; ++i) { m[i] = bf4(mr[c.lane + 64 * i]); x[i] = (l == 0) ? xs[c.lane + 64 * i] : ldx(xr + (c.lane + 64 * i) * 4); } } };
.LBB0_1048:
	s_nop 0
	global_load_dwordx2 v[190:191], v[62:63], off offset:3072
	s_and_b64 vcc, exec, s[0:1]
	s_mov_b64 s[60:61], -1
	s_cbranch_vccnz .LBB0_1050
	s_waitcnt vmcnt(7)
	v_cvt_f32_f16_e32 v58, v60
	v_cvt_f32_f16_sdwa v59, v60 dst_sel:DWORD dst_unused:UNUSED_PAD src0_sel:WORD_1
	v_cvt_f32_f16_e32 v60, v61
	v_cvt_f32_f16_sdwa v61, v61 dst_sel:DWORD dst_unused:UNUSED_PAD src0_sel:WORD_1
	s_cbranch_execnz .LBB0_1052
	s_branch .LBB0_1051

; __device__ __forceinline__ f32x4 ldx(const _Float16* p) { const h16x4 h = *(const h16x4*)p; return __builtin_convertvector(h, f32x4); }
; __device__ __forceinline__ f32x4 bf4(const u32x2 w) { return (f32x4){__uint_as_float(w[0] << 16), __uint_as_float(w[0] & 0xffff0000u), __uint_as_float(w[1] << 16), __uint_as_float(w[1] & 0xffff0000u)}; }
; __device__ __forceinline__ void phase_postmix(const Params& p, const Ctx& c, int l, bool last) {
;     ...
; #pragma unroll
;       for (int i = 0; i < 8; ++i) { m[i] = bf4(mr[c.lane + 64 * i]); x[i] = (l == 0) ? xs[c.lane + 64 * i] : ldx(xr + (c.lane + 64 * i) * 4); } } };
.LBB0_1052:
	s_nop 0
	global_load_dwordx2 v[192:193], v[62:63], off offset:3584
	s_and_b64 vcc, exec, s[0:1]
	s_mov_b64 s[60:61], -1
	s_cbranch_vccnz .LBB0_1054
	s_waitcnt vmcnt(7)
	v_cvt_f32_f16_e32 v62, v64
	v_cvt_f32_f16_sdwa v63, v64 dst_sel:DWORD dst_unused:UNUSED_PAD src0_sel:WORD_1
	v_cvt_f32_f16_e32 v64, v65
	v_cvt_f32_f16_sdwa v65, v65 dst_sel:DWORD dst_unused:UNUSED_PAD src0_sel:WORD_1
	s_cbranch_execz .LBB0_1055
	s_branch .LBB0_1056
